# v2 + static s_setprio 1 for the leading wave half (wr==0 flag) in all four GEMM phases incl. P8, K-loop flips deleted
# baseline (speedup 1.0000x reference)
.LBB0_210:
	s_and_b32 s3, s3, 3
	s_lshl_b32 s12, s2, 13
	s_lshl_b32 s13, s3, 9
	s_add_u32 s4, s88, 0x188800
	s_addc_u32 s5, s89, 0
	s_add_i32 m0, s68, 0x18000
	v_lshl_add_u64 v[8:9], s[4:5], 0, v[132:133]
	s_waitcnt vmcnt(2)
	s_barrier
	global_load_lds_dwordx4 v[8:9], off
	v_lshl_add_u64 v[8:9], s[4:5], 0, v[136:137]
	s_add_i32 m0, s68, 0x1a000
	s_mov_b64 s[52:53], 0x80
	s_add_i32 s8, s68, 0x8000
	s_add_i32 s9, s68, 0xa000
	global_load_lds_dwordx4 v[8:9], off
	v_lshl_add_u64 v[2:3], v[2:3], 0, s[52:53]
	s_mov_b32 m0, s8
	s_add_u32 s4, s88, 0x189000
	global_load_lds_dwordx4 v[2:3], off
	v_lshl_add_u64 v[2:3], v[4:5], 0, s[52:53]
	s_mov_b32 m0, s9
	s_addc_u32 s5, s89, 0
	global_load_lds_dwordx4 v[2:3], off
	s_add_i32 m0, s68, 0x1c000
	v_lshl_add_u64 v[2:3], s[4:5], 0, v[132:133]
	global_load_lds_dwordx4 v[2:3], off
	v_lshl_add_u64 v[2:3], s[4:5], 0, v[136:137]
	s_add_i32 m0, s68, 0x1e000
	v_and_b32_e32 v1, 15, v6
	global_load_lds_dwordx4 v[2:3], off
	v_bfe_u32 v2, v6, 4, 2
	v_lshlrev_b32_e32 v3, 4, v2
	v_lshlrev_b32_e32 v4, 2, v6
	v_lshl_or_b32 v3, v1, 6, v3
	v_and_b32_e32 v4, 32, v4
	v_lshlrev_b32_e32 v2, 11, v2
	v_lshlrev_b32_e32 v1, 4, v1
	s_cmpk_lt_u32 s0, 0x100
	v_bitop3_b32 v3, v3, s12, v4 bitop3:0xde
	v_or3_b32 v1, s13, v1, v2
	s_cselect_b64 s[66:67], -1, 0
	v_bfe_u32 v2, v6, 2, 4
	v_and_b32_e32 v4, 3, v6
	s_ashr_i32 s0, s92, 31
	v_lshl_or_b32 v143, s2, 6, v2
	v_lshlrev_b32_e32 v2, 3, v4
	v_writelane_b32 v249, s0, 58
	v_lshl_or_b32 v144, s3, 5, v2
	v_readlane_b32 s2, v249, 2
	s_mov_b32 s0, s2
	s_ashr_i32 s2, s2, 31
	v_readlane_b32 s3, v249, 3
	v_writelane_b32 v249, s2, 60
	s_and_b32 s2, s0, 7
	s_waitcnt vmcnt(6)
	v_writelane_b32 v249, s2, 61
	s_bfe_u32 s2, s0, 0x30003
	v_and_b32_e32 v5, 60, v6
	v_writelane_b32 v249, s2, 62
	s_ashr_i32 s0, s0, 6
	v_lshl_or_b32 v142, v4, 6, v5
	v_writelane_b32 v249, s0, 63
	v_mov_b32_e32 v146, s1
	s_add_i32 s0, 0, 0x10000
	s_add_i32 s1, 0, 0x14000
	v_add_u32_e32 v145, 0, v3
	s_movk_i32 s72, 0x6080
	v_mov_b64_e32 v[138:139], 0x8ff
	s_barrier
	s_setprio 0
	s_and_b64 vcc, exec, s[66:67]
	s_cbranch_vccz .Lpl_done0
	s_setprio 1

.LBB0_519:
	s_add_u32 s19, s50, 0x108000
	s_addc_u32 s52, s51, 0
	s_and_b32 s18, s4, 3
	s_lshl_b32 s20, s3, 13
	s_lshl_b32 s21, s18, 9
	s_add_u32 s4, s78, 0x88800
	s_addc_u32 s5, s79, 0
	s_add_i32 m0, s94, 0x18000
	v_lshl_add_u64 v[8:9], s[4:5], 0, v[140:141]
	s_waitcnt vmcnt(2)
	s_barrier
	global_load_lds_dwordx4 v[8:9], off
	v_lshl_add_u64 v[8:9], s[4:5], 0, v[144:145]
	s_add_i32 m0, s94, 0x1a000
	s_mov_b64 s[56:57], 0x80
	s_add_i32 s53, s94, 0x8000
	s_add_i32 s92, s94, 0xa000
	global_load_lds_dwordx4 v[8:9], off
	v_lshl_add_u64 v[2:3], v[2:3], 0, s[56:57]
	s_mov_b32 m0, s53
	s_add_u32 s4, s78, 0x89000
	global_load_lds_dwordx4 v[2:3], off
	v_lshl_add_u64 v[2:3], v[4:5], 0, s[56:57]
	s_mov_b32 m0, s92
	s_addc_u32 s5, s79, 0
	global_load_lds_dwordx4 v[2:3], off
	s_add_i32 m0, s94, 0x1c000
	v_lshl_add_u64 v[2:3], s[4:5], 0, v[140:141]
	global_load_lds_dwordx4 v[2:3], off
	v_lshl_add_u64 v[2:3], s[4:5], 0, v[144:145]
	s_add_i32 m0, s94, 0x1e000
	v_and_b32_e32 v1, 15, v6
	global_load_lds_dwordx4 v[2:3], off
	v_bfe_u32 v2, v6, 4, 2
	v_lshlrev_b32_e32 v3, 4, v2
	v_lshlrev_b32_e32 v4, 2, v6
	v_lshl_or_b32 v3, v1, 6, v3
	v_and_b32_e32 v4, 32, v4
	v_lshlrev_b32_e32 v2, 11, v2
	v_lshlrev_b32_e32 v1, 4, v1
	v_bitop3_b32 v18, v3, s20, v4 bitop3:0xde
	v_or3_b32 v1, s21, v1, v2
	v_and_b32_e32 v2, 3, v6
	v_and_b32_e32 v3, 60, v6
	s_cmpk_lt_u32 s14, 0x100
	v_lshl_or_b32 v184, v2, 6, v3
	v_bfe_u32 v3, v6, 2, 4
	v_lshlrev_b32_e32 v2, 3, v2
	v_readlane_b32 s4, v249, 49
	s_cselect_b64 s[58:59], -1, 0
	v_lshl_or_b32 v185, s18, 5, v2
	v_lshl_or_b32 v2, s3, 6, v3
	s_ashr_i32 s3, s4, 31
	v_readlane_b32 s5, v249, 50
	v_writelane_b32 v249, s3, 60
	s_waitcnt vmcnt(6)
	v_or_b32_e32 v4, 16, v2
	v_readlane_b32 s4, v249, 2
	s_ashr_i32 s3, s4, 31
	v_readlane_b32 s5, v249, 3
	v_writelane_b32 v249, s3, 61
	s_and_b32 s3, s4, 4
	v_writelane_b32 v249, s3, 62
	s_bfe_u32 s3, s4, 0x30003
	v_writelane_b32 v249, s3, 63
	s_lshl_b32 s3, s4, 2
	s_and_b32 s3, s3, 12
	s_ashr_i32 s4, s4, 6
	v_or_b32_e32 v6, 32, v2
	v_or_b32_e32 v8, 48, v2
	v_add_u32_e32 v10, 0x80, v2
	v_add_u32_e32 v12, 0x90, v2
	v_add_u32_e32 v14, 0xa0, v2
	v_add_u32_e32 v16, 0xb0, v2
	s_add_i32 s3, s3, s4
	v_ashrrev_i32_e32 v3, 31, v2
	v_ashrrev_i32_e32 v5, 31, v4
	v_ashrrev_i32_e32 v7, 31, v6
	v_ashrrev_i32_e32 v9, 31, v8
	v_ashrrev_i32_e32 v11, 31, v10
	v_ashrrev_i32_e32 v13, 31, v12
	v_ashrrev_i32_e32 v15, 31, v14
	v_ashrrev_i32_e32 v17, 31, v16
	v_writelane_b32 v248, s3, 3
	s_movk_i32 s3, 0x2080
	v_lshlrev_b64 v[146:147], 14, v[2:3]
	v_lshlrev_b64 v[148:149], 14, v[4:5]
	v_lshlrev_b64 v[150:151], 14, v[6:7]
	v_lshlrev_b64 v[152:153], 14, v[8:9]
	v_lshlrev_b64 v[154:155], 14, v[10:11]
	v_lshlrev_b64 v[156:157], 14, v[12:13]
	v_lshlrev_b64 v[158:159], 14, v[14:15]
	v_lshlrev_b64 v[160:161], 14, v[16:17]
	v_mad_i64_i32 v[162:163], s[4:5], v2, s3, 0
	v_mad_i64_i32 v[164:165], s[4:5], v4, s3, 0
	v_mad_i64_i32 v[166:167], s[4:5], v6, s3, 0
	v_mad_i64_i32 v[168:169], s[4:5], v8, s3, 0
	v_mad_i64_i32 v[170:171], s[4:5], v10, s3, 0
	v_mad_i64_i32 v[172:173], s[4:5], v12, s3, 0
	v_mad_i64_i32 v[174:175], s[4:5], v14, s3, 0
	v_mad_i64_i32 v[176:177], s[4:5], v16, s3, 0
	v_mov_b32_e32 v187, s2
	s_add_i32 s93, 0, 0x10000
	s_add_i32 s18, 0, 0x14000
	v_add_u32_e32 v186, 0, v18
	v_mov_b64_e32 v[178:179], 0x2ff
	s_mov_b32 s36, 0
	s_barrier
	s_setprio 0
	s_and_b64 vcc, exec, s[58:59]
	s_cbranch_vccz .Lpl_done1
	s_setprio 1

.LBB0_757:
	s_and_b32 s22, s4, 3
	s_lshl_b32 s23, s3, 13
	s_lshl_b32 s24, s22, 9
	s_add_u32 s4, s56, 0x208800
	s_addc_u32 s5, s57, 0
	s_add_i32 m0, s36, 0x18000
	v_lshl_add_u64 v[8:9], s[4:5], 0, v[132:133]
	s_waitcnt vmcnt(2)
	s_barrier
	global_load_lds_dwordx4 v[8:9], off
	v_lshl_add_u64 v[8:9], s[4:5], 0, v[136:137]
	s_add_i32 m0, s36, 0x1a000
	s_mov_b64 s[14:15], 0x80
	s_add_i32 s77, s36, 0x8000
	s_add_i32 s78, s36, 0xa000
	global_load_lds_dwordx4 v[8:9], off
	v_lshl_add_u64 v[2:3], v[2:3], 0, s[14:15]
	s_mov_b32 m0, s77
	s_add_u32 s4, s56, 0x209000
	global_load_lds_dwordx4 v[2:3], off
	v_lshl_add_u64 v[2:3], v[4:5], 0, s[14:15]
	s_mov_b32 m0, s78
	s_addc_u32 s5, s57, 0
	global_load_lds_dwordx4 v[2:3], off
	s_add_i32 m0, s36, 0x1c000
	v_lshl_add_u64 v[2:3], s[4:5], 0, v[132:133]
	global_load_lds_dwordx4 v[2:3], off
	v_lshl_add_u64 v[2:3], s[4:5], 0, v[136:137]
	s_add_i32 m0, s36, 0x1e000
	v_and_b32_e32 v1, 15, v6
	global_load_lds_dwordx4 v[2:3], off
	v_bfe_u32 v2, v6, 4, 2
	v_lshlrev_b32_e32 v3, 4, v2
	v_lshl_or_b32 v3, v1, 6, v3
	v_lshlrev_b32_e32 v4, 2, v6
	v_lshlrev_b32_e32 v2, 11, v2
	v_lshlrev_b32_e32 v1, 4, v1
	v_and_b32_e32 v4, 32, v4
	v_or3_b32 v1, s24, v1, v2
	s_cmpk_lt_u32 s20, 0x100
	v_bfe_u32 v2, v6, 2, 4
	v_readlane_b32 s4, v249, 2
	v_bitop3_b32 v3, v3, s23, v4 bitop3:0xde
	s_waitcnt vmcnt(6)
	s_cselect_b64 s[30:31], -1, 0
	v_and_b32_e32 v4, 3, v6
	v_lshl_or_b32 v143, s3, 6, v2
	s_lshl_b32 s3, s4, 2
	v_and_b32_e32 v5, 60, v6
	v_lshlrev_b32_e32 v2, 3, v4
	s_and_b32 s82, s3, 28
	s_ashr_i32 s3, s4, 6
	v_lshl_or_b32 v142, v4, 6, v5
	v_lshl_or_b32 v144, s22, 5, v2
	s_ashr_i32 s79, s92, 31
	s_ashr_i32 s80, s4, 31
	s_bfe_u32 s81, s4, 0x30003
	s_add_i32 s82, s82, s3
	v_mov_b32_e32 v146, s2
	s_add_i32 s83, 0, 0x10000
	s_add_i32 s84, 0, 0x14000
	v_add_u32_e32 v145, 0, v3
	s_mov_b32 s85, 0x8080
	v_mov_b64_e32 v[138:139], 0xbff
	s_barrier
	v_readlane_b32 s5, v249, 3
	s_setprio 0
	s_and_b64 vcc, exec, s[30:31]
	s_cbranch_vccz .Lpl_done2
	s_setprio 1

.LBB0_894:
	s_add_u32 s76, s50, 0x114000
	s_addc_u32 s77, s51, 0
	s_and_b32 s18, s12, 3
	s_lshl_b32 s15, s3, 13
	s_lshl_b32 s22, s18, 9
	s_add_u32 s12, s40, 0x88800
	s_addc_u32 s13, s41, 0
	s_add_i32 m0, s33, 0x18000
	v_lshl_add_u64 v[6:7], s[12:13], 0, v[138:139]
	s_waitcnt vmcnt(2)
	s_barrier
	global_load_lds_dwordx4 v[6:7], off
	v_lshl_add_u64 v[6:7], s[12:13], 0, v[142:143]
	s_add_i32 m0, s33, 0x1a000
	s_mov_b64 s[12:13], 0x80
	s_add_i32 s78, s33, 0x8000
	s_add_i32 s79, s33, 0xa000
	global_load_lds_dwordx4 v[6:7], off
	v_lshl_add_u64 v[2:3], v[2:3], 0, s[12:13]
	s_mov_b32 m0, s78
	s_add_u32 s20, s40, 0x89000
	global_load_lds_dwordx4 v[2:3], off
	v_lshl_add_u64 v[2:3], v[4:5], 0, s[12:13]
	s_mov_b32 m0, s79
	s_addc_u32 s21, s41, 0
	global_load_lds_dwordx4 v[2:3], off
	s_add_i32 m0, s33, 0x1c000
	v_lshl_add_u64 v[2:3], s[20:21], 0, v[138:139]
	global_load_lds_dwordx4 v[2:3], off
	v_lshl_add_u64 v[2:3], s[20:21], 0, v[142:143]
	s_add_i32 m0, s33, 0x1e000
	v_and_b32_e32 v1, 15, v0
	global_load_lds_dwordx4 v[2:3], off
	v_bfe_u32 v2, v0, 4, 2
	v_lshlrev_b32_e32 v3, 4, v2
	v_lshl_or_b32 v3, v1, 6, v3
	v_lshlrev_b32_e32 v4, 2, v0
	v_lshlrev_b32_e32 v2, 11, v2
	v_lshlrev_b32_e32 v1, 4, v1
	v_and_b32_e32 v4, 32, v4
	v_or3_b32 v182, s22, v1, v2
	s_cmpk_lt_u32 s14, 0x100
	v_and_b32_e32 v1, 3, v0
	v_and_b32_e32 v2, 60, v0
	v_bfe_u32 v0, v0, 2, 4
	v_readlane_b32 s20, v249, 2
	v_bitop3_b32 v16, v3, s15, v4 bitop3:0xde
	s_cselect_b64 s[14:15], -1, 0
	v_lshl_or_b32 v0, s3, 6, v0
	s_lshl_b32 s3, s20, 2
	s_waitcnt vmcnt(6)
	v_lshlrev_b32_e32 v3, 3, v1
	v_lshl_or_b32 v184, v1, 6, v2
	v_or_b32_e32 v2, 16, v0
	v_or_b32_e32 v4, 32, v0
	v_or_b32_e32 v6, 48, v0
	v_add_u32_e32 v8, 0x80, v0
	v_add_u32_e32 v10, 0x90, v0
	v_add_u32_e32 v12, 0xa0, v0
	v_add_u32_e32 v14, 0xb0, v0
	s_and_b32 s84, s3, 12
	s_ashr_i32 s3, s20, 6
	v_lshl_or_b32 v183, s18, 5, v3
	v_ashrrev_i32_e32 v1, 31, v0
	v_ashrrev_i32_e32 v3, 31, v2
	v_ashrrev_i32_e32 v5, 31, v4
	v_ashrrev_i32_e32 v7, 31, v6
	v_ashrrev_i32_e32 v9, 31, v8
	v_ashrrev_i32_e32 v11, 31, v10
	v_ashrrev_i32_e32 v13, 31, v12
	v_ashrrev_i32_e32 v15, 31, v14
	v_readlane_b32 s21, v249, 3
	s_add_i32 s84, s84, s3
	s_movk_i32 s3, 0x2080
	v_lshlrev_b64 v[144:145], 14, v[0:1]
	v_lshlrev_b64 v[146:147], 14, v[2:3]
	v_lshlrev_b64 v[148:149], 14, v[4:5]
	v_lshlrev_b64 v[150:151], 14, v[6:7]
	v_lshlrev_b64 v[152:153], 14, v[8:9]
	v_lshlrev_b64 v[154:155], 14, v[10:11]
	v_lshlrev_b64 v[156:157], 14, v[12:13]
	v_lshlrev_b64 v[158:159], 14, v[14:15]
	s_ashr_i32 s80, s92, 31
	s_ashr_i32 s81, s20, 31
	s_and_b32 s82, s20, 4
	s_bfe_u32 s83, s20, 0x30003
	v_mad_i64_i32 v[160:161], s[20:21], v0, s3, 0
	v_mad_i64_i32 v[162:163], s[20:21], v2, s3, 0
	v_mad_i64_i32 v[164:165], s[20:21], v4, s3, 0
	v_mad_i64_i32 v[166:167], s[20:21], v6, s3, 0
	v_mad_i64_i32 v[168:169], s[20:21], v8, s3, 0
	v_mad_i64_i32 v[170:171], s[20:21], v10, s3, 0
	v_mad_i64_i32 v[172:173], s[20:21], v12, s3, 0
	v_mad_i64_i32 v[174:175], s[20:21], v14, s3, 0
	v_mov_b32_e32 v186, s2
	s_movk_i32 s18, 0x61
	s_add_i32 s36, 0, 0x10000
	s_add_i32 s37, 0, 0x14000
	v_add_u32_e32 v185, 0, v16
	v_mov_b64_e32 v[176:177], 0x2ff
	s_barrier
	s_setprio 0
	s_and_b64 vcc, exec, s[14:15]
	s_cbranch_vccz .Lpl_done3
	s_setprio 1
